# GEMM K-loops: odd half-step A-fragment ds_reads issued behind the even half-step MFMAs (LDS latency hidden across half-steps)
# speedup vs baseline: 1.0080x; 1.0080x over previous
.Lg1_nda1:
.Lg1_sada1:
	v_add_u32_e32 v244, s28, v242
	v_add_u32_e32 v245, s28, v243
	ds_read_b128 v[198:201], v244 offset:0
	ds_read_b128 v[202:205], v244 offset:2048
	ds_read_b128 v[210:213], v244 offset:4096
	ds_read_b128 v[214:217], v244 offset:6144
	ds_read_b128 v[218:221], v244 offset:8192
	ds_read_b128 v[222:225], v244 offset:10240
	ds_read_b128 v[226:229], v244 offset:12288
	ds_read_b128 v[230:233], v244 offset:14336
	s_waitcnt lgkmcnt(4)
	v_mfma_f32_16x16x32_bf16 v[0:3], v[128:131], v[198:201], v[0:3]
	v_mfma_f32_16x16x32_bf16 v[32:35], v[132:135], v[198:201], v[32:35]
	v_mfma_f32_16x16x32_bf16 v[64:67], v[136:139], v[198:201], v[64:67]
	v_mfma_f32_16x16x32_bf16 v[96:99], v[140:143], v[198:201], v[96:99]
	v_mfma_f32_16x16x32_bf16 v[4:7], v[128:131], v[202:205], v[4:7]
	v_mfma_f32_16x16x32_bf16 v[36:39], v[132:135], v[202:205], v[36:39]
	v_mfma_f32_16x16x32_bf16 v[68:71], v[136:139], v[202:205], v[68:71]
	v_mfma_f32_16x16x32_bf16 v[100:103], v[140:143], v[202:205], v[100:103]
	v_mfma_f32_16x16x32_bf16 v[8:11], v[128:131], v[210:213], v[8:11]
	v_mfma_f32_16x16x32_bf16 v[40:43], v[132:135], v[210:213], v[40:43]
	v_mfma_f32_16x16x32_bf16 v[72:75], v[136:139], v[210:213], v[72:75]
	v_mfma_f32_16x16x32_bf16 v[104:107], v[140:143], v[210:213], v[104:107]
	v_mfma_f32_16x16x32_bf16 v[12:15], v[128:131], v[214:217], v[12:15]
	v_mfma_f32_16x16x32_bf16 v[44:47], v[132:135], v[214:217], v[44:47]
	v_mfma_f32_16x16x32_bf16 v[76:79], v[136:139], v[214:217], v[76:79]
	v_mfma_f32_16x16x32_bf16 v[108:111], v[140:143], v[214:217], v[108:111]
	ds_read_b128 v[198:201], v245 offset:0
	ds_read_b128 v[202:205], v245 offset:2048
	ds_read_b128 v[210:213], v245 offset:4096
	ds_read_b128 v[214:217], v245 offset:6144
	s_waitcnt lgkmcnt(4)
	v_mfma_f32_16x16x32_bf16 v[16:19], v[128:131], v[218:221], v[16:19]
	v_mfma_f32_16x16x32_bf16 v[48:51], v[132:135], v[218:221], v[48:51]
	v_mfma_f32_16x16x32_bf16 v[80:83], v[136:139], v[218:221], v[80:83]
	v_mfma_f32_16x16x32_bf16 v[112:115], v[140:143], v[218:221], v[112:115]
	v_mfma_f32_16x16x32_bf16 v[20:23], v[128:131], v[222:225], v[20:23]
	v_mfma_f32_16x16x32_bf16 v[52:55], v[132:135], v[222:225], v[52:55]
	v_mfma_f32_16x16x32_bf16 v[84:87], v[136:139], v[222:225], v[84:87]
	v_mfma_f32_16x16x32_bf16 v[116:119], v[140:143], v[222:225], v[116:119]
	v_mfma_f32_16x16x32_bf16 v[24:27], v[128:131], v[226:229], v[24:27]
	v_mfma_f32_16x16x32_bf16 v[56:59], v[132:135], v[226:229], v[56:59]
	v_mfma_f32_16x16x32_bf16 v[88:91], v[136:139], v[226:229], v[88:91]
	v_mfma_f32_16x16x32_bf16 v[120:123], v[140:143], v[226:229], v[120:123]
	v_mfma_f32_16x16x32_bf16 v[28:31], v[128:131], v[230:233], v[28:31]
	v_mfma_f32_16x16x32_bf16 v[60:63], v[132:135], v[230:233], v[60:63]
	v_mfma_f32_16x16x32_bf16 v[92:95], v[136:139], v[230:233], v[92:95]
	v_mfma_f32_16x16x32_bf16 v[124:127], v[140:143], v[230:233], v[124:127]
	ds_read_b128 v[218:221], v245 offset:8192
	ds_read_b128 v[222:225], v245 offset:10240
	ds_read_b128 v[226:229], v245 offset:12288
	ds_read_b128 v[230:233], v245 offset:14336
	s_waitcnt vmcnt(16)
	global_load_dwordx4 v[128:131], v238, s[56:57]
	global_load_dwordx4 v[132:135], v239, s[56:57]
	global_load_dwordx4 v[136:139], v240, s[56:57]
	global_load_dwordx4 v[140:143], v241, s[56:57]
	s_cmp_eq_u32 s25, 31
	s_cbranch_scc1 .Lg1_sww2
	s_add_u32 s56, s56, 1024
	s_addc_u32 s57, s57, 0
	s_branch .Lg1_swdw2

.Lg1_ndw2:
.Lg1_swdw2:
	s_add_i32 s25, s25, 1
	s_waitcnt lgkmcnt(4)
	v_mfma_f32_16x16x32_bf16 v[0:3], v[144:147], v[198:201], v[0:3]
	v_mfma_f32_16x16x32_bf16 v[32:35], v[148:151], v[198:201], v[32:35]
	v_mfma_f32_16x16x32_bf16 v[64:67], v[152:155], v[198:201], v[64:67]
	v_mfma_f32_16x16x32_bf16 v[96:99], v[156:159], v[198:201], v[96:99]
	v_mfma_f32_16x16x32_bf16 v[4:7], v[144:147], v[202:205], v[4:7]
	v_mfma_f32_16x16x32_bf16 v[36:39], v[148:151], v[202:205], v[36:39]
	v_mfma_f32_16x16x32_bf16 v[68:71], v[152:155], v[202:205], v[68:71]
	v_mfma_f32_16x16x32_bf16 v[100:103], v[156:159], v[202:205], v[100:103]
	v_mfma_f32_16x16x32_bf16 v[8:11], v[144:147], v[210:213], v[8:11]
	v_mfma_f32_16x16x32_bf16 v[40:43], v[148:151], v[210:213], v[40:43]
	v_mfma_f32_16x16x32_bf16 v[72:75], v[152:155], v[210:213], v[72:75]
	v_mfma_f32_16x16x32_bf16 v[104:107], v[156:159], v[210:213], v[104:107]
	v_mfma_f32_16x16x32_bf16 v[12:15], v[144:147], v[214:217], v[12:15]
	v_mfma_f32_16x16x32_bf16 v[44:47], v[148:151], v[214:217], v[44:47]
	v_mfma_f32_16x16x32_bf16 v[76:79], v[152:155], v[214:217], v[76:79]
	v_mfma_f32_16x16x32_bf16 v[108:111], v[156:159], v[214:217], v[108:111]
	s_waitcnt lgkmcnt(0)
	v_mfma_f32_16x16x32_bf16 v[16:19], v[144:147], v[218:221], v[16:19]
	v_mfma_f32_16x16x32_bf16 v[48:51], v[148:151], v[218:221], v[48:51]
	v_mfma_f32_16x16x32_bf16 v[80:83], v[152:155], v[218:221], v[80:83]
	v_mfma_f32_16x16x32_bf16 v[112:115], v[156:159], v[218:221], v[112:115]
	v_mfma_f32_16x16x32_bf16 v[20:23], v[144:147], v[222:225], v[20:23]
	v_mfma_f32_16x16x32_bf16 v[52:55], v[148:151], v[222:225], v[52:55]
	v_mfma_f32_16x16x32_bf16 v[84:87], v[152:155], v[222:225], v[84:87]
	v_mfma_f32_16x16x32_bf16 v[116:119], v[156:159], v[222:225], v[116:119]
	v_mfma_f32_16x16x32_bf16 v[24:27], v[144:147], v[226:229], v[24:27]
	v_mfma_f32_16x16x32_bf16 v[56:59], v[148:151], v[226:229], v[56:59]
	v_mfma_f32_16x16x32_bf16 v[88:91], v[152:155], v[226:229], v[88:91]
	v_mfma_f32_16x16x32_bf16 v[120:123], v[156:159], v[226:229], v[120:123]
	v_mfma_f32_16x16x32_bf16 v[28:31], v[144:147], v[230:233], v[28:31]
	v_mfma_f32_16x16x32_bf16 v[60:63], v[148:151], v[230:233], v[60:63]
	v_mfma_f32_16x16x32_bf16 v[92:95], v[152:155], v[230:233], v[92:95]
	v_mfma_f32_16x16x32_bf16 v[124:127], v[156:159], v[230:233], v[124:127]
	s_add_i32 s28, s28, 0x4000
	s_cmp_lt_u32 s28, 0xc000
	s_cselect_b32 s28, s28, 0
	s_add_i32 s27, s27, 0x4000
	s_cmp_lt_u32 s27, 0xc000
	s_cselect_b32 s27, s27, 0
	s_add_i32 s29, s29, 1
	s_waitcnt vmcnt(12)
	s_barrier
	global_load_dwordx4 v[144:147], v238, s[56:57]
	global_load_dwordx4 v[148:151], v239, s[56:57]
	global_load_dwordx4 v[152:155], v240, s[56:57]
	global_load_dwordx4 v[156:159], v241, s[56:57]
	s_cmp_eq_u32 s25, 31
	s_cbranch_scc1 .Lg1_sww3
	s_add_u32 s56, s56, 1024
	s_addc_u32 s57, s57, 0
	s_branch .Lg1_swdw3

.Lg1_nda4:
.Lg1_sada4:
	v_add_u32_e32 v244, s28, v242
	v_add_u32_e32 v245, s28, v243
	ds_read_b128 v[198:201], v244 offset:0
	ds_read_b128 v[202:205], v244 offset:2048
	ds_read_b128 v[210:213], v244 offset:4096
	ds_read_b128 v[214:217], v244 offset:6144
	ds_read_b128 v[218:221], v244 offset:8192
	ds_read_b128 v[222:225], v244 offset:10240
	ds_read_b128 v[226:229], v244 offset:12288
	ds_read_b128 v[230:233], v244 offset:14336
	s_waitcnt lgkmcnt(4)
	v_mfma_f32_16x16x32_bf16 v[0:3], v[160:163], v[198:201], v[0:3]
	v_mfma_f32_16x16x32_bf16 v[32:35], v[164:167], v[198:201], v[32:35]
	v_mfma_f32_16x16x32_bf16 v[64:67], v[168:171], v[198:201], v[64:67]
	v_mfma_f32_16x16x32_bf16 v[96:99], v[172:175], v[198:201], v[96:99]
	v_mfma_f32_16x16x32_bf16 v[4:7], v[160:163], v[202:205], v[4:7]
	v_mfma_f32_16x16x32_bf16 v[36:39], v[164:167], v[202:205], v[36:39]
	v_mfma_f32_16x16x32_bf16 v[68:71], v[168:171], v[202:205], v[68:71]
	v_mfma_f32_16x16x32_bf16 v[100:103], v[172:175], v[202:205], v[100:103]
	v_mfma_f32_16x16x32_bf16 v[8:11], v[160:163], v[210:213], v[8:11]
	v_mfma_f32_16x16x32_bf16 v[40:43], v[164:167], v[210:213], v[40:43]
	v_mfma_f32_16x16x32_bf16 v[72:75], v[168:171], v[210:213], v[72:75]
	v_mfma_f32_16x16x32_bf16 v[104:107], v[172:175], v[210:213], v[104:107]
	v_mfma_f32_16x16x32_bf16 v[12:15], v[160:163], v[214:217], v[12:15]
	v_mfma_f32_16x16x32_bf16 v[44:47], v[164:167], v[214:217], v[44:47]
	v_mfma_f32_16x16x32_bf16 v[76:79], v[168:171], v[214:217], v[76:79]
	v_mfma_f32_16x16x32_bf16 v[108:111], v[172:175], v[214:217], v[108:111]
	ds_read_b128 v[198:201], v245 offset:0
	ds_read_b128 v[202:205], v245 offset:2048
	ds_read_b128 v[210:213], v245 offset:4096
	ds_read_b128 v[214:217], v245 offset:6144
	s_waitcnt lgkmcnt(4)
	v_mfma_f32_16x16x32_bf16 v[16:19], v[160:163], v[218:221], v[16:19]
	v_mfma_f32_16x16x32_bf16 v[48:51], v[164:167], v[218:221], v[48:51]
	v_mfma_f32_16x16x32_bf16 v[80:83], v[168:171], v[218:221], v[80:83]
	v_mfma_f32_16x16x32_bf16 v[112:115], v[172:175], v[218:221], v[112:115]
	v_mfma_f32_16x16x32_bf16 v[20:23], v[160:163], v[222:225], v[20:23]
	v_mfma_f32_16x16x32_bf16 v[52:55], v[164:167], v[222:225], v[52:55]
	v_mfma_f32_16x16x32_bf16 v[84:87], v[168:171], v[222:225], v[84:87]
	v_mfma_f32_16x16x32_bf16 v[116:119], v[172:175], v[222:225], v[116:119]
	v_mfma_f32_16x16x32_bf16 v[24:27], v[160:163], v[226:229], v[24:27]
	v_mfma_f32_16x16x32_bf16 v[56:59], v[164:167], v[226:229], v[56:59]
	v_mfma_f32_16x16x32_bf16 v[88:91], v[168:171], v[226:229], v[88:91]
	v_mfma_f32_16x16x32_bf16 v[120:123], v[172:175], v[226:229], v[120:123]
	v_mfma_f32_16x16x32_bf16 v[28:31], v[160:163], v[230:233], v[28:31]
	v_mfma_f32_16x16x32_bf16 v[60:63], v[164:167], v[230:233], v[60:63]
	v_mfma_f32_16x16x32_bf16 v[92:95], v[168:171], v[230:233], v[92:95]
	v_mfma_f32_16x16x32_bf16 v[124:127], v[172:175], v[230:233], v[124:127]
	ds_read_b128 v[218:221], v245 offset:8192
	ds_read_b128 v[222:225], v245 offset:10240
	ds_read_b128 v[226:229], v245 offset:12288
	ds_read_b128 v[230:233], v245 offset:14336
	s_waitcnt vmcnt(16)
	global_load_dwordx4 v[160:163], v238, s[56:57]
	global_load_dwordx4 v[164:167], v239, s[56:57]
	global_load_dwordx4 v[168:171], v240, s[56:57]
	global_load_dwordx4 v[172:175], v241, s[56:57]
	s_cmp_eq_u32 s25, 31
	s_cbranch_scc1 .Lg1_sww5
	s_add_u32 s56, s56, 1024
	s_addc_u32 s57, s57, 0
	s_branch .Lg1_swdw5

.Lg1_ndw5:
.Lg1_swdw5:
	s_add_i32 s25, s25, 1
	s_waitcnt lgkmcnt(4)
	v_mfma_f32_16x16x32_bf16 v[0:3], v[176:179], v[198:201], v[0:3]
	v_mfma_f32_16x16x32_bf16 v[32:35], v[182:185], v[198:201], v[32:35]
	v_mfma_f32_16x16x32_bf16 v[64:67], v[186:189], v[198:201], v[64:67]
	v_mfma_f32_16x16x32_bf16 v[96:99], v[194:197], v[198:201], v[96:99]
	v_mfma_f32_16x16x32_bf16 v[4:7], v[176:179], v[202:205], v[4:7]
	v_mfma_f32_16x16x32_bf16 v[36:39], v[182:185], v[202:205], v[36:39]
	v_mfma_f32_16x16x32_bf16 v[68:71], v[186:189], v[202:205], v[68:71]
	v_mfma_f32_16x16x32_bf16 v[100:103], v[194:197], v[202:205], v[100:103]
	v_mfma_f32_16x16x32_bf16 v[8:11], v[176:179], v[210:213], v[8:11]
	v_mfma_f32_16x16x32_bf16 v[40:43], v[182:185], v[210:213], v[40:43]
	v_mfma_f32_16x16x32_bf16 v[72:75], v[186:189], v[210:213], v[72:75]
	v_mfma_f32_16x16x32_bf16 v[104:107], v[194:197], v[210:213], v[104:107]
	v_mfma_f32_16x16x32_bf16 v[12:15], v[176:179], v[214:217], v[12:15]
	v_mfma_f32_16x16x32_bf16 v[44:47], v[182:185], v[214:217], v[44:47]
	v_mfma_f32_16x16x32_bf16 v[76:79], v[186:189], v[214:217], v[76:79]
	v_mfma_f32_16x16x32_bf16 v[108:111], v[194:197], v[214:217], v[108:111]
	s_waitcnt lgkmcnt(0)
	v_mfma_f32_16x16x32_bf16 v[16:19], v[176:179], v[218:221], v[16:19]
	v_mfma_f32_16x16x32_bf16 v[48:51], v[182:185], v[218:221], v[48:51]
	v_mfma_f32_16x16x32_bf16 v[80:83], v[186:189], v[218:221], v[80:83]
	v_mfma_f32_16x16x32_bf16 v[112:115], v[194:197], v[218:221], v[112:115]
	v_mfma_f32_16x16x32_bf16 v[20:23], v[176:179], v[222:225], v[20:23]
	v_mfma_f32_16x16x32_bf16 v[52:55], v[182:185], v[222:225], v[52:55]
	v_mfma_f32_16x16x32_bf16 v[84:87], v[186:189], v[222:225], v[84:87]
	v_mfma_f32_16x16x32_bf16 v[116:119], v[194:197], v[222:225], v[116:119]
	v_mfma_f32_16x16x32_bf16 v[24:27], v[176:179], v[226:229], v[24:27]
	v_mfma_f32_16x16x32_bf16 v[56:59], v[182:185], v[226:229], v[56:59]
	v_mfma_f32_16x16x32_bf16 v[88:91], v[186:189], v[226:229], v[88:91]
	v_mfma_f32_16x16x32_bf16 v[120:123], v[194:197], v[226:229], v[120:123]
	v_mfma_f32_16x16x32_bf16 v[28:31], v[176:179], v[230:233], v[28:31]
	v_mfma_f32_16x16x32_bf16 v[60:63], v[182:185], v[230:233], v[60:63]
	v_mfma_f32_16x16x32_bf16 v[92:95], v[186:189], v[230:233], v[92:95]
	v_mfma_f32_16x16x32_bf16 v[124:127], v[194:197], v[230:233], v[124:127]
	s_add_i32 s28, s28, 0x4000
	s_cmp_lt_u32 s28, 0xc000
	s_cselect_b32 s28, s28, 0
	s_add_i32 s27, s27, 0x4000
	s_cmp_lt_u32 s27, 0xc000
	s_cselect_b32 s27, s27, 0
	s_add_i32 s29, s29, 1
	s_cmp_lt_u32 s29, 16
	s_cbranch_scc1 .Lg1_loop
	s_mov_b32 s32, 0
	s_add_i32 s0, s30, s36
	s_cmp_lt_i32 s0, s31
	s_cbranch_scc0 .Lg1_nf
	s_cmp_eq_u64 s[2:3], 0
	s_cbranch_scc0 .Lg1_nf
	s_mov_b32 s32, 0x600d0000
	s_or_b32 s32, s32, s28

.Lg2_nda1:
.Lg2_sada1:
	v_add_u32_e32 v244, s56, v242
	v_add_u32_e32 v245, s56, v243
	ds_read_b128 v[200:203], v244 offset:0
	ds_read_b128 v[204:207], v244 offset:2048
	ds_read_b128 v[210:213], v244 offset:4096
	ds_read_b128 v[214:217], v244 offset:6144
	ds_read_b128 v[218:221], v244 offset:8192
	ds_read_b128 v[222:225], v244 offset:10240
	ds_read_b128 v[226:229], v244 offset:12288
	ds_read_b128 v[230:233], v244 offset:14336
	s_waitcnt lgkmcnt(4)
	v_mfma_f32_16x16x32_bf16 v[0:3], v[128:131], v[200:203], v[0:3]
	v_mfma_f32_16x16x32_bf16 v[32:35], v[132:135], v[200:203], v[32:35]
	v_mfma_f32_16x16x32_bf16 v[64:67], v[136:139], v[200:203], v[64:67]
	v_mfma_f32_16x16x32_bf16 v[96:99], v[140:143], v[200:203], v[96:99]
	v_mfma_f32_16x16x32_bf16 v[4:7], v[128:131], v[204:207], v[4:7]
	v_mfma_f32_16x16x32_bf16 v[36:39], v[132:135], v[204:207], v[36:39]
	v_mfma_f32_16x16x32_bf16 v[68:71], v[136:139], v[204:207], v[68:71]
	v_mfma_f32_16x16x32_bf16 v[100:103], v[140:143], v[204:207], v[100:103]
	v_mfma_f32_16x16x32_bf16 v[8:11], v[128:131], v[210:213], v[8:11]
	v_mfma_f32_16x16x32_bf16 v[40:43], v[132:135], v[210:213], v[40:43]
	v_mfma_f32_16x16x32_bf16 v[72:75], v[136:139], v[210:213], v[72:75]
	v_mfma_f32_16x16x32_bf16 v[104:107], v[140:143], v[210:213], v[104:107]
	v_mfma_f32_16x16x32_bf16 v[12:15], v[128:131], v[214:217], v[12:15]
	v_mfma_f32_16x16x32_bf16 v[44:47], v[132:135], v[214:217], v[44:47]
	v_mfma_f32_16x16x32_bf16 v[76:79], v[136:139], v[214:217], v[76:79]
	v_mfma_f32_16x16x32_bf16 v[108:111], v[140:143], v[214:217], v[108:111]
	ds_read_b128 v[200:203], v245 offset:0
	ds_read_b128 v[204:207], v245 offset:2048
	ds_read_b128 v[210:213], v245 offset:4096
	ds_read_b128 v[214:217], v245 offset:6144
	s_waitcnt lgkmcnt(4)
	v_mfma_f32_16x16x32_bf16 v[16:19], v[128:131], v[218:221], v[16:19]
	v_mfma_f32_16x16x32_bf16 v[48:51], v[132:135], v[218:221], v[48:51]
	v_mfma_f32_16x16x32_bf16 v[80:83], v[136:139], v[218:221], v[80:83]
	v_mfma_f32_16x16x32_bf16 v[112:115], v[140:143], v[218:221], v[112:115]
	v_mfma_f32_16x16x32_bf16 v[20:23], v[128:131], v[222:225], v[20:23]
	v_mfma_f32_16x16x32_bf16 v[52:55], v[132:135], v[222:225], v[52:55]
	v_mfma_f32_16x16x32_bf16 v[84:87], v[136:139], v[222:225], v[84:87]
	v_mfma_f32_16x16x32_bf16 v[116:119], v[140:143], v[222:225], v[116:119]
	v_mfma_f32_16x16x32_bf16 v[24:27], v[128:131], v[226:229], v[24:27]
	v_mfma_f32_16x16x32_bf16 v[56:59], v[132:135], v[226:229], v[56:59]
	v_mfma_f32_16x16x32_bf16 v[88:91], v[136:139], v[226:229], v[88:91]
	v_mfma_f32_16x16x32_bf16 v[120:123], v[140:143], v[226:229], v[120:123]
	v_mfma_f32_16x16x32_bf16 v[28:31], v[128:131], v[230:233], v[28:31]
	v_mfma_f32_16x16x32_bf16 v[60:63], v[132:135], v[230:233], v[60:63]
	v_mfma_f32_16x16x32_bf16 v[92:95], v[136:139], v[230:233], v[92:95]
	v_mfma_f32_16x16x32_bf16 v[124:127], v[140:143], v[230:233], v[124:127]
	ds_read_b128 v[218:221], v245 offset:8192
	ds_read_b128 v[222:225], v245 offset:10240
	ds_read_b128 v[226:229], v245 offset:12288
	ds_read_b128 v[230:233], v245 offset:14336
	s_waitcnt vmcnt(16)
	global_load_dwordx4 v[128:131], v238, s[54:55]
	global_load_dwordx4 v[132:135], v239, s[54:55]
	global_load_dwordx4 v[136:139], v240, s[54:55]
	global_load_dwordx4 v[140:143], v241, s[54:55]
	s_cmp_eq_u32 s59, 31
	s_cbranch_scc1 .Lg2_sww2
	s_add_u32 s54, s54, 1024
	s_addc_u32 s55, s55, 0
	s_branch .Lg2_swdw2

.Lg2_wndw2:
.Lg2_swdw2:
	s_add_i32 s59, s59, 1
	s_waitcnt lgkmcnt(4)
	v_mfma_f32_16x16x32_bf16 v[0:3], v[144:147], v[200:203], v[0:3]
	v_mfma_f32_16x16x32_bf16 v[32:35], v[148:151], v[200:203], v[32:35]
	v_mfma_f32_16x16x32_bf16 v[64:67], v[152:155], v[200:203], v[64:67]
	v_mfma_f32_16x16x32_bf16 v[96:99], v[156:159], v[200:203], v[96:99]
	v_mfma_f32_16x16x32_bf16 v[4:7], v[144:147], v[204:207], v[4:7]
	v_mfma_f32_16x16x32_bf16 v[36:39], v[148:151], v[204:207], v[36:39]
	v_mfma_f32_16x16x32_bf16 v[68:71], v[152:155], v[204:207], v[68:71]
	v_mfma_f32_16x16x32_bf16 v[100:103], v[156:159], v[204:207], v[100:103]
	v_mfma_f32_16x16x32_bf16 v[8:11], v[144:147], v[210:213], v[8:11]
	v_mfma_f32_16x16x32_bf16 v[40:43], v[148:151], v[210:213], v[40:43]
	v_mfma_f32_16x16x32_bf16 v[72:75], v[152:155], v[210:213], v[72:75]
	v_mfma_f32_16x16x32_bf16 v[104:107], v[156:159], v[210:213], v[104:107]
	v_mfma_f32_16x16x32_bf16 v[12:15], v[144:147], v[214:217], v[12:15]
	v_mfma_f32_16x16x32_bf16 v[44:47], v[148:151], v[214:217], v[44:47]
	v_mfma_f32_16x16x32_bf16 v[76:79], v[152:155], v[214:217], v[76:79]
	v_mfma_f32_16x16x32_bf16 v[108:111], v[156:159], v[214:217], v[108:111]
	s_waitcnt lgkmcnt(0)
	v_mfma_f32_16x16x32_bf16 v[16:19], v[144:147], v[218:221], v[16:19]
	v_mfma_f32_16x16x32_bf16 v[48:51], v[148:151], v[218:221], v[48:51]
	v_mfma_f32_16x16x32_bf16 v[80:83], v[152:155], v[218:221], v[80:83]
	v_mfma_f32_16x16x32_bf16 v[112:115], v[156:159], v[218:221], v[112:115]
	v_mfma_f32_16x16x32_bf16 v[20:23], v[144:147], v[222:225], v[20:23]
	v_mfma_f32_16x16x32_bf16 v[52:55], v[148:151], v[222:225], v[52:55]
	v_mfma_f32_16x16x32_bf16 v[84:87], v[152:155], v[222:225], v[84:87]
	v_mfma_f32_16x16x32_bf16 v[116:119], v[156:159], v[222:225], v[116:119]
	v_mfma_f32_16x16x32_bf16 v[24:27], v[144:147], v[226:229], v[24:27]
	v_mfma_f32_16x16x32_bf16 v[56:59], v[148:151], v[226:229], v[56:59]
	v_mfma_f32_16x16x32_bf16 v[88:91], v[152:155], v[226:229], v[88:91]
	v_mfma_f32_16x16x32_bf16 v[120:123], v[156:159], v[226:229], v[120:123]
	v_mfma_f32_16x16x32_bf16 v[28:31], v[144:147], v[230:233], v[28:31]
	v_mfma_f32_16x16x32_bf16 v[60:63], v[148:151], v[230:233], v[60:63]
	v_mfma_f32_16x16x32_bf16 v[92:95], v[152:155], v[230:233], v[92:95]
	v_mfma_f32_16x16x32_bf16 v[124:127], v[156:159], v[230:233], v[124:127]
	s_add_i32 s56, s56, 0x4000
	s_cmp_lt_u32 s56, 0xc000
	s_cselect_b32 s56, s56, 0
	s_add_i32 s57, s57, 0x4000
	s_cmp_lt_u32 s57, 0xc000
	s_cselect_b32 s57, s57, 0
	s_add_i32 s58, s58, 1
	s_waitcnt vmcnt(12)
	s_barrier
	global_load_dwordx4 v[144:147], v238, s[54:55]
	global_load_dwordx4 v[148:151], v239, s[54:55]
	global_load_dwordx4 v[152:155], v240, s[54:55]
	global_load_dwordx4 v[156:159], v241, s[54:55]
	s_cmp_eq_u32 s59, 31
	s_cbranch_scc1 .Lg2_sww3
	s_add_u32 s54, s54, 1024
	s_addc_u32 s55, s55, 0
	s_branch .Lg2_swdw3

.Lg2_nda4:
.Lg2_sada4:
	v_add_u32_e32 v244, s56, v242
	v_add_u32_e32 v245, s56, v243
	ds_read_b128 v[200:203], v244 offset:0
	ds_read_b128 v[204:207], v244 offset:2048
	ds_read_b128 v[210:213], v244 offset:4096
	ds_read_b128 v[214:217], v244 offset:6144
	ds_read_b128 v[218:221], v244 offset:8192
	ds_read_b128 v[222:225], v244 offset:10240
	ds_read_b128 v[226:229], v244 offset:12288
	ds_read_b128 v[230:233], v244 offset:14336
	s_waitcnt lgkmcnt(4)
	v_mfma_f32_16x16x32_bf16 v[0:3], v[160:163], v[200:203], v[0:3]
	v_mfma_f32_16x16x32_bf16 v[32:35], v[164:167], v[200:203], v[32:35]
	v_mfma_f32_16x16x32_bf16 v[64:67], v[168:171], v[200:203], v[64:67]
	v_mfma_f32_16x16x32_bf16 v[96:99], v[172:175], v[200:203], v[96:99]
	v_mfma_f32_16x16x32_bf16 v[4:7], v[160:163], v[204:207], v[4:7]
	v_mfma_f32_16x16x32_bf16 v[36:39], v[164:167], v[204:207], v[36:39]
	v_mfma_f32_16x16x32_bf16 v[68:71], v[168:171], v[204:207], v[68:71]
	v_mfma_f32_16x16x32_bf16 v[100:103], v[172:175], v[204:207], v[100:103]
	v_mfma_f32_16x16x32_bf16 v[8:11], v[160:163], v[210:213], v[8:11]
	v_mfma_f32_16x16x32_bf16 v[40:43], v[164:167], v[210:213], v[40:43]
	v_mfma_f32_16x16x32_bf16 v[72:75], v[168:171], v[210:213], v[72:75]
	v_mfma_f32_16x16x32_bf16 v[104:107], v[172:175], v[210:213], v[104:107]
	v_mfma_f32_16x16x32_bf16 v[12:15], v[160:163], v[214:217], v[12:15]
	v_mfma_f32_16x16x32_bf16 v[44:47], v[164:167], v[214:217], v[44:47]
	v_mfma_f32_16x16x32_bf16 v[76:79], v[168:171], v[214:217], v[76:79]
	v_mfma_f32_16x16x32_bf16 v[108:111], v[172:175], v[214:217], v[108:111]
	ds_read_b128 v[200:203], v245 offset:0
	ds_read_b128 v[204:207], v245 offset:2048
	ds_read_b128 v[210:213], v245 offset:4096
	ds_read_b128 v[214:217], v245 offset:6144
	s_waitcnt lgkmcnt(4)
	v_mfma_f32_16x16x32_bf16 v[16:19], v[160:163], v[218:221], v[16:19]
	v_mfma_f32_16x16x32_bf16 v[48:51], v[164:167], v[218:221], v[48:51]
	v_mfma_f32_16x16x32_bf16 v[80:83], v[168:171], v[218:221], v[80:83]
	v_mfma_f32_16x16x32_bf16 v[112:115], v[172:175], v[218:221], v[112:115]
	v_mfma_f32_16x16x32_bf16 v[20:23], v[160:163], v[222:225], v[20:23]
	v_mfma_f32_16x16x32_bf16 v[52:55], v[164:167], v[222:225], v[52:55]
	v_mfma_f32_16x16x32_bf16 v[84:87], v[168:171], v[222:225], v[84:87]
	v_mfma_f32_16x16x32_bf16 v[116:119], v[172:175], v[222:225], v[116:119]
	v_mfma_f32_16x16x32_bf16 v[24:27], v[160:163], v[226:229], v[24:27]
	v_mfma_f32_16x16x32_bf16 v[56:59], v[164:167], v[226:229], v[56:59]
	v_mfma_f32_16x16x32_bf16 v[88:91], v[168:171], v[226:229], v[88:91]
	v_mfma_f32_16x16x32_bf16 v[120:123], v[172:175], v[226:229], v[120:123]
	v_mfma_f32_16x16x32_bf16 v[28:31], v[160:163], v[230:233], v[28:31]
	v_mfma_f32_16x16x32_bf16 v[60:63], v[164:167], v[230:233], v[60:63]
	v_mfma_f32_16x16x32_bf16 v[92:95], v[168:171], v[230:233], v[92:95]
	v_mfma_f32_16x16x32_bf16 v[124:127], v[172:175], v[230:233], v[124:127]
	ds_read_b128 v[218:221], v245 offset:8192
	ds_read_b128 v[222:225], v245 offset:10240
	ds_read_b128 v[226:229], v245 offset:12288
	ds_read_b128 v[230:233], v245 offset:14336
	s_waitcnt vmcnt(16)
	global_load_dwordx4 v[160:163], v238, s[54:55]
	global_load_dwordx4 v[164:167], v239, s[54:55]
	global_load_dwordx4 v[168:171], v240, s[54:55]
	global_load_dwordx4 v[172:175], v241, s[54:55]
	s_cmp_eq_u32 s59, 31
	s_cbranch_scc1 .Lg2_sww5
	s_add_u32 s54, s54, 1024
	s_addc_u32 s55, s55, 0
	s_branch .Lg2_swdw5

.Lg2_wndw5:
.Lg2_swdw5:
	s_add_i32 s59, s59, 1
	s_waitcnt lgkmcnt(4)
	v_mfma_f32_16x16x32_bf16 v[0:3], v[176:179], v[200:203], v[0:3]
	v_mfma_f32_16x16x32_bf16 v[32:35], v[184:187], v[200:203], v[32:35]
	v_mfma_f32_16x16x32_bf16 v[64:67], v[188:191], v[200:203], v[64:67]
	v_mfma_f32_16x16x32_bf16 v[96:99], v[196:199], v[200:203], v[96:99]
	v_mfma_f32_16x16x32_bf16 v[4:7], v[176:179], v[204:207], v[4:7]
	v_mfma_f32_16x16x32_bf16 v[36:39], v[184:187], v[204:207], v[36:39]
	v_mfma_f32_16x16x32_bf16 v[68:71], v[188:191], v[204:207], v[68:71]
	v_mfma_f32_16x16x32_bf16 v[100:103], v[196:199], v[204:207], v[100:103]
	v_mfma_f32_16x16x32_bf16 v[8:11], v[176:179], v[210:213], v[8:11]
	v_mfma_f32_16x16x32_bf16 v[40:43], v[184:187], v[210:213], v[40:43]
	v_mfma_f32_16x16x32_bf16 v[72:75], v[188:191], v[210:213], v[72:75]
	v_mfma_f32_16x16x32_bf16 v[104:107], v[196:199], v[210:213], v[104:107]
	v_mfma_f32_16x16x32_bf16 v[12:15], v[176:179], v[214:217], v[12:15]
	v_mfma_f32_16x16x32_bf16 v[44:47], v[184:187], v[214:217], v[44:47]
	v_mfma_f32_16x16x32_bf16 v[76:79], v[188:191], v[214:217], v[76:79]
	v_mfma_f32_16x16x32_bf16 v[108:111], v[196:199], v[214:217], v[108:111]
	s_waitcnt lgkmcnt(0)
	v_mfma_f32_16x16x32_bf16 v[16:19], v[176:179], v[218:221], v[16:19]
	v_mfma_f32_16x16x32_bf16 v[48:51], v[184:187], v[218:221], v[48:51]
	v_mfma_f32_16x16x32_bf16 v[80:83], v[188:191], v[218:221], v[80:83]
	v_mfma_f32_16x16x32_bf16 v[112:115], v[196:199], v[218:221], v[112:115]
	v_mfma_f32_16x16x32_bf16 v[20:23], v[176:179], v[222:225], v[20:23]
	v_mfma_f32_16x16x32_bf16 v[52:55], v[184:187], v[222:225], v[52:55]
	v_mfma_f32_16x16x32_bf16 v[84:87], v[188:191], v[222:225], v[84:87]
	v_mfma_f32_16x16x32_bf16 v[116:119], v[196:199], v[222:225], v[116:119]
	v_mfma_f32_16x16x32_bf16 v[24:27], v[176:179], v[226:229], v[24:27]
	v_mfma_f32_16x16x32_bf16 v[56:59], v[184:187], v[226:229], v[56:59]
	v_mfma_f32_16x16x32_bf16 v[88:91], v[188:191], v[226:229], v[88:91]
	v_mfma_f32_16x16x32_bf16 v[120:123], v[196:199], v[226:229], v[120:123]
	v_mfma_f32_16x16x32_bf16 v[28:31], v[176:179], v[230:233], v[28:31]
	v_mfma_f32_16x16x32_bf16 v[60:63], v[184:187], v[230:233], v[60:63]
	v_mfma_f32_16x16x32_bf16 v[92:95], v[188:191], v[230:233], v[92:95]
	v_mfma_f32_16x16x32_bf16 v[124:127], v[196:199], v[230:233], v[124:127]
	s_add_i32 s56, s56, 0x4000
	s_cmp_lt_u32 s56, 0xc000
	s_cselect_b32 s56, s56, 0
	s_add_i32 s57, s57, 0x4000
	s_cmp_lt_u32 s57, 0xc000
	s_cselect_b32 s57, s57, 0
	s_add_i32 s58, s58, 1
	s_cmp_lt_u32 s58, 16
	s_cbranch_scc1 .Lg2_loop
	s_nop 7
	s_nop 7
	v_and_b32_e32 v200, 63, v208
	v_lshrrev_b32_e32 v201, 6, v208
	v_and_b32_e32 v202, 15, v200
	v_lshrrev_b32_e32 v203, 4, v200
	s_add_i32 s24, s21, s20
	s_and_b32 s24, s24, 3
	s_lshl_b32 s24, s24, 8
	s_lshl_b32 s8, s20, 7
	v_add_u32_e32 v204, s8, v202
	v_lshlrev_b32_e32 v205, 2, v203
	v_lshl_add_u32 v205, v201, 6, v205
	v_add_u32_e32 v205, s24, v205
	v_lshlrev_b32_e32 v206, 12, v204
	v_lshl_add_u32 v206, v205, 2, v206
	v_mov_b32_e32 v245, s63
	v_add_co_u32_e32 v244, vcc, s62, v206
	s_nop 1
	v_addc_co_u32_e32 v245, vcc, 0, v245, vcc
	v_lshlrev_b32_e32 v206, 11, v204
	v_lshl_add_u32 v206, v205, 1, v206
	v_add_u32_e32 v206, 0x1e000000, v206
	v_mov_b32_e32 v243, s93
	v_add_co_u32_e32 v242, vcc, s92, v206
	s_nop 1
	v_addc_co_u32_e32 v243, vcc, 0, v243, vcc
	global_load_dwordx4 v[200:203], v[244:245], off offset:0
	global_load_dwordx4 v[204:207], v[244:245], off offset:64
	global_load_dwordx4 v[210:213], v[244:245], off offset:128
	global_load_dwordx4 v[214:217], v[244:245], off offset:192
	v_add_co_u32_e32 v244, vcc, 0x10000, v244
	s_nop 1
	v_addc_co_u32_e32 v245, vcc, 0, v245, vcc
	global_load_dwordx4 v[218:221], v[244:245], off offset:0
	global_load_dwordx4 v[222:225], v[244:245], off offset:64
	global_load_dwordx4 v[226:229], v[244:245], off offset:128
	global_load_dwordx4 v[230:233], v[244:245], off offset:192
	v_add_co_u32_e32 v244, vcc, 0x10000, v244
	s_nop 1
	v_addc_co_u32_e32 v245, vcc, 0, v245, vcc
	s_waitcnt vmcnt(4)
	v_pk_add_f32 v[200:201], v[200:201], v[0:1]
	v_pk_add_f32 v[202:203], v[202:203], v[2:3]
	v_fmac_f32_e32 v246, v200, v200
	v_fmac_f32_e32 v246, v201, v201
	v_fmac_f32_e32 v246, v202, v202
	v_fmac_f32_e32 v246, v203, v203
	v_cvt_pk_bf16_f32 v200, v200, v201
	v_cvt_pk_bf16_f32 v201, v202, v203
	global_store_dwordx2 v[242:243], v[200:201], off offset:0
	v_pk_add_f32 v[204:205], v[204:205], v[32:33]
	v_pk_add_f32 v[206:207], v[206:207], v[34:35]
	v_fmac_f32_e32 v246, v204, v204
	v_fmac_f32_e32 v246, v205, v205
	v_fmac_f32_e32 v246, v206, v206
	v_fmac_f32_e32 v246, v207, v207
	v_cvt_pk_bf16_f32 v204, v204, v205
	v_cvt_pk_bf16_f32 v205, v206, v207
	global_store_dwordx2 v[242:243], v[204:205], off offset:32
	v_pk_add_f32 v[210:211], v[210:211], v[64:65]
	v_pk_add_f32 v[212:213], v[212:213], v[66:67]
	v_fmac_f32_e32 v246, v210, v210
	v_fmac_f32_e32 v246, v211, v211
	v_fmac_f32_e32 v246, v212, v212
	v_fmac_f32_e32 v246, v213, v213
	v_cvt_pk_bf16_f32 v210, v210, v211
	v_cvt_pk_bf16_f32 v211, v212, v213
	global_store_dwordx2 v[242:243], v[210:211], off offset:64
	v_pk_add_f32 v[214:215], v[214:215], v[96:97]
	v_pk_add_f32 v[216:217], v[216:217], v[98:99]
	v_fmac_f32_e32 v246, v214, v214
	v_fmac_f32_e32 v246, v215, v215
	v_fmac_f32_e32 v246, v216, v216
	v_fmac_f32_e32 v246, v217, v217
	v_cvt_pk_bf16_f32 v214, v214, v215
	v_cvt_pk_bf16_f32 v215, v216, v217
	global_store_dwordx2 v[242:243], v[214:215], off offset:96
	v_add_co_u32_e32 v242, vcc, 0x8000, v242
	s_nop 1
	v_addc_co_u32_e32 v243, vcc, 0, v243, vcc
	global_load_dwordx4 v[200:203], v[244:245], off offset:0
	global_load_dwordx4 v[204:207], v[244:245], off offset:64
	global_load_dwordx4 v[210:213], v[244:245], off offset:128
	global_load_dwordx4 v[214:217], v[244:245], off offset:192
	v_add_co_u32_e32 v244, vcc, 0x10000, v244
	s_nop 1
	v_addc_co_u32_e32 v245, vcc, 0, v245, vcc
	s_waitcnt vmcnt(8)
	v_pk_add_f32 v[218:219], v[218:219], v[4:5]
	v_pk_add_f32 v[220:221], v[220:221], v[6:7]
	v_fmac_f32_e32 v247, v218, v218
	v_fmac_f32_e32 v247, v219, v219
	v_fmac_f32_e32 v247, v220, v220
	v_fmac_f32_e32 v247, v221, v221
	v_cvt_pk_bf16_f32 v218, v218, v219
	v_cvt_pk_bf16_f32 v219, v220, v221
	global_store_dwordx2 v[242:243], v[218:219], off offset:0
	v_pk_add_f32 v[222:223], v[222:223], v[36:37]
	v_pk_add_f32 v[224:225], v[224:225], v[38:39]
	v_fmac_f32_e32 v247, v222, v222
	v_fmac_f32_e32 v247, v223, v223
	v_fmac_f32_e32 v247, v224, v224
	v_fmac_f32_e32 v247, v225, v225
	v_cvt_pk_bf16_f32 v222, v222, v223
	v_cvt_pk_bf16_f32 v223, v224, v225
	global_store_dwordx2 v[242:243], v[222:223], off offset:32
	v_pk_add_f32 v[226:227], v[226:227], v[68:69]
	v_pk_add_f32 v[228:229], v[228:229], v[70:71]
	v_fmac_f32_e32 v247, v226, v226
	v_fmac_f32_e32 v247, v227, v227
	v_fmac_f32_e32 v247, v228, v228
	v_fmac_f32_e32 v247, v229, v229
	v_cvt_pk_bf16_f32 v226, v226, v227
	v_cvt_pk_bf16_f32 v227, v228, v229
	global_store_dwordx2 v[242:243], v[226:227], off offset:64
	v_pk_add_f32 v[230:231], v[230:231], v[100:101]
	v_pk_add_f32 v[232:233], v[232:233], v[102:103]
	v_fmac_f32_e32 v247, v230, v230
	v_fmac_f32_e32 v247, v231, v231
	v_fmac_f32_e32 v247, v232, v232
	v_fmac_f32_e32 v247, v233, v233
	v_cvt_pk_bf16_f32 v230, v230, v231
	v_cvt_pk_bf16_f32 v231, v232, v233
	global_store_dwordx2 v[242:243], v[230:231], off offset:96
	v_add_co_u32_e32 v242, vcc, 0x8000, v242
	s_nop 1
	v_addc_co_u32_e32 v243, vcc, 0, v243, vcc
	global_load_dwordx4 v[218:221], v[244:245], off offset:0
	global_load_dwordx4 v[222:225], v[244:245], off offset:64
	global_load_dwordx4 v[226:229], v[244:245], off offset:128
	global_load_dwordx4 v[230:233], v[244:245], off offset:192
	v_add_co_u32_e32 v244, vcc, 0x10000, v244
	s_nop 1
	v_addc_co_u32_e32 v245, vcc, 0, v245, vcc
	s_waitcnt vmcnt(8)
	v_pk_add_f32 v[200:201], v[200:201], v[8:9]
	v_pk_add_f32 v[202:203], v[202:203], v[10:11]
	v_fmac_f32_e32 v248, v200, v200
	v_fmac_f32_e32 v248, v201, v201
	v_fmac_f32_e32 v248, v202, v202
	v_fmac_f32_e32 v248, v203, v203
	v_cvt_pk_bf16_f32 v200, v200, v201
	v_cvt_pk_bf16_f32 v201, v202, v203
	global_store_dwordx2 v[242:243], v[200:201], off offset:0
	v_pk_add_f32 v[204:205], v[204:205], v[40:41]
	v_pk_add_f32 v[206:207], v[206:207], v[42:43]
	v_fmac_f32_e32 v248, v204, v204
	v_fmac_f32_e32 v248, v205, v205
	v_fmac_f32_e32 v248, v206, v206
	v_fmac_f32_e32 v248, v207, v207
	v_cvt_pk_bf16_f32 v204, v204, v205
	v_cvt_pk_bf16_f32 v205, v206, v207
	global_store_dwordx2 v[242:243], v[204:205], off offset:32
	v_pk_add_f32 v[210:211], v[210:211], v[72:73]
	v_pk_add_f32 v[212:213], v[212:213], v[74:75]
	v_fmac_f32_e32 v248, v210, v210
	v_fmac_f32_e32 v248, v211, v211
	v_fmac_f32_e32 v248, v212, v212
	v_fmac_f32_e32 v248, v213, v213
	v_cvt_pk_bf16_f32 v210, v210, v211
	v_cvt_pk_bf16_f32 v211, v212, v213
	global_store_dwordx2 v[242:243], v[210:211], off offset:64
	v_pk_add_f32 v[214:215], v[214:215], v[104:105]
	v_pk_add_f32 v[216:217], v[216:217], v[106:107]
	v_fmac_f32_e32 v248, v214, v214
	v_fmac_f32_e32 v248, v215, v215
	v_fmac_f32_e32 v248, v216, v216
	v_fmac_f32_e32 v248, v217, v217
	v_cvt_pk_bf16_f32 v214, v214, v215
	v_cvt_pk_bf16_f32 v215, v216, v217
	global_store_dwordx2 v[242:243], v[214:215], off offset:96
	v_add_co_u32_e32 v242, vcc, 0x8000, v242
	s_nop 1
	v_addc_co_u32_e32 v243, vcc, 0, v243, vcc
	global_load_dwordx4 v[200:203], v[244:245], off offset:0
	global_load_dwordx4 v[204:207], v[244:245], off offset:64
	global_load_dwordx4 v[210:213], v[244:245], off offset:128
	global_load_dwordx4 v[214:217], v[244:245], off offset:192
	v_add_co_u32_e32 v244, vcc, 0x10000, v244
	s_nop 1
	v_addc_co_u32_e32 v245, vcc, 0, v245, vcc
	s_waitcnt vmcnt(8)
	v_pk_add_f32 v[218:219], v[218:219], v[12:13]
	v_pk_add_f32 v[220:221], v[220:221], v[14:15]
	v_fmac_f32_e32 v249, v218, v218
	v_fmac_f32_e32 v249, v219, v219
	v_fmac_f32_e32 v249, v220, v220
	v_fmac_f32_e32 v249, v221, v221
	v_cvt_pk_bf16_f32 v218, v218, v219
	v_cvt_pk_bf16_f32 v219, v220, v221
	global_store_dwordx2 v[242:243], v[218:219], off offset:0
	v_pk_add_f32 v[222:223], v[222:223], v[44:45]
	v_pk_add_f32 v[224:225], v[224:225], v[46:47]
	v_fmac_f32_e32 v249, v222, v222
	v_fmac_f32_e32 v249, v223, v223
	v_fmac_f32_e32 v249, v224, v224
	v_fmac_f32_e32 v249, v225, v225
	v_cvt_pk_bf16_f32 v222, v222, v223
	v_cvt_pk_bf16_f32 v223, v224, v225
	global_store_dwordx2 v[242:243], v[222:223], off offset:32
	v_pk_add_f32 v[226:227], v[226:227], v[76:77]
	v_pk_add_f32 v[228:229], v[228:229], v[78:79]
	v_fmac_f32_e32 v249, v226, v226
	v_fmac_f32_e32 v249, v227, v227
	v_fmac_f32_e32 v249, v228, v228
	v_fmac_f32_e32 v249, v229, v229
	v_cvt_pk_bf16_f32 v226, v226, v227
	v_cvt_pk_bf16_f32 v227, v228, v229
	global_store_dwordx2 v[242:243], v[226:227], off offset:64
	v_pk_add_f32 v[230:231], v[230:231], v[108:109]
	v_pk_add_f32 v[232:233], v[232:233], v[110:111]
	v_fmac_f32_e32 v249, v230, v230
	v_fmac_f32_e32 v249, v231, v231
	v_fmac_f32_e32 v249, v232, v232
	v_fmac_f32_e32 v249, v233, v233
	v_cvt_pk_bf16_f32 v230, v230, v231
	v_cvt_pk_bf16_f32 v231, v232, v233
	global_store_dwordx2 v[242:243], v[230:231], off offset:96
	v_add_co_u32_e32 v242, vcc, 0x8000, v242
	s_nop 1
	v_addc_co_u32_e32 v243, vcc, 0, v243, vcc
	global_load_dwordx4 v[218:221], v[244:245], off offset:0
	global_load_dwordx4 v[222:225], v[244:245], off offset:64
	global_load_dwordx4 v[226:229], v[244:245], off offset:128
	global_load_dwordx4 v[230:233], v[244:245], off offset:192
	v_add_co_u32_e32 v244, vcc, 0x10000, v244
	s_nop 1
	v_addc_co_u32_e32 v245, vcc, 0, v245, vcc
	s_waitcnt vmcnt(8)
	v_pk_add_f32 v[200:201], v[200:201], v[16:17]
	v_pk_add_f32 v[202:203], v[202:203], v[18:19]
	v_fmac_f32_e32 v250, v200, v200
	v_fmac_f32_e32 v250, v201, v201
	v_fmac_f32_e32 v250, v202, v202
	v_fmac_f32_e32 v250, v203, v203
	v_cvt_pk_bf16_f32 v200, v200, v201
	v_cvt_pk_bf16_f32 v201, v202, v203
	global_store_dwordx2 v[242:243], v[200:201], off offset:0
	v_pk_add_f32 v[204:205], v[204:205], v[48:49]
	v_pk_add_f32 v[206:207], v[206:207], v[50:51]
	v_fmac_f32_e32 v250, v204, v204
	v_fmac_f32_e32 v250, v205, v205
	v_fmac_f32_e32 v250, v206, v206
	v_fmac_f32_e32 v250, v207, v207
	v_cvt_pk_bf16_f32 v204, v204, v205
	v_cvt_pk_bf16_f32 v205, v206, v207
	global_store_dwordx2 v[242:243], v[204:205], off offset:32
	v_pk_add_f32 v[210:211], v[210:211], v[80:81]
	v_pk_add_f32 v[212:213], v[212:213], v[82:83]
	v_fmac_f32_e32 v250, v210, v210
	v_fmac_f32_e32 v250, v211, v211
	v_fmac_f32_e32 v250, v212, v212
	v_fmac_f32_e32 v250, v213, v213
	v_cvt_pk_bf16_f32 v210, v210, v211
	v_cvt_pk_bf16_f32 v211, v212, v213
	global_store_dwordx2 v[242:243], v[210:211], off offset:64
	v_pk_add_f32 v[214:215], v[214:215], v[112:113]
	v_pk_add_f32 v[216:217], v[216:217], v[114:115]
	v_fmac_f32_e32 v250, v214, v214
	v_fmac_f32_e32 v250, v215, v215
	v_fmac_f32_e32 v250, v216, v216
	v_fmac_f32_e32 v250, v217, v217
	v_cvt_pk_bf16_f32 v214, v214, v215
	v_cvt_pk_bf16_f32 v215, v216, v217
	global_store_dwordx2 v[242:243], v[214:215], off offset:96
	v_add_co_u32_e32 v242, vcc, 0x8000, v242
	s_nop 1
	v_addc_co_u32_e32 v243, vcc, 0, v243, vcc
	global_load_dwordx4 v[200:203], v[244:245], off offset:0
	global_load_dwordx4 v[204:207], v[244:245], off offset:64
	global_load_dwordx4 v[210:213], v[244:245], off offset:128
	global_load_dwordx4 v[214:217], v[244:245], off offset:192
	v_add_co_u32_e32 v244, vcc, 0x10000, v244
	s_nop 1
	v_addc_co_u32_e32 v245, vcc, 0, v245, vcc
	s_waitcnt vmcnt(8)
	v_pk_add_f32 v[218:219], v[218:219], v[20:21]
	v_pk_add_f32 v[220:221], v[220:221], v[22:23]
	v_fmac_f32_e32 v251, v218, v218
	v_fmac_f32_e32 v251, v219, v219
	v_fmac_f32_e32 v251, v220, v220
	v_fmac_f32_e32 v251, v221, v221
	v_cvt_pk_bf16_f32 v218, v218, v219
	v_cvt_pk_bf16_f32 v219, v220, v221
	global_store_dwordx2 v[242:243], v[218:219], off offset:0
	v_pk_add_f32 v[222:223], v[222:223], v[52:53]
	v_pk_add_f32 v[224:225], v[224:225], v[54:55]
	v_fmac_f32_e32 v251, v222, v222
	v_fmac_f32_e32 v251, v223, v223
	v_fmac_f32_e32 v251, v224, v224
	v_fmac_f32_e32 v251, v225, v225
	v_cvt_pk_bf16_f32 v222, v222, v223
	v_cvt_pk_bf16_f32 v223, v224, v225
	global_store_dwordx2 v[242:243], v[222:223], off offset:32
	v_pk_add_f32 v[226:227], v[226:227], v[84:85]
	v_pk_add_f32 v[228:229], v[228:229], v[86:87]
	v_fmac_f32_e32 v251, v226, v226
	v_fmac_f32_e32 v251, v227, v227
	v_fmac_f32_e32 v251, v228, v228
	v_fmac_f32_e32 v251, v229, v229
	v_cvt_pk_bf16_f32 v226, v226, v227
	v_cvt_pk_bf16_f32 v227, v228, v229
	global_store_dwordx2 v[242:243], v[226:227], off offset:64
	v_pk_add_f32 v[230:231], v[230:231], v[116:117]
	v_pk_add_f32 v[232:233], v[232:233], v[118:119]
	v_fmac_f32_e32 v251, v230, v230
	v_fmac_f32_e32 v251, v231, v231
	v_fmac_f32_e32 v251, v232, v232
	v_fmac_f32_e32 v251, v233, v233
	v_cvt_pk_bf16_f32 v230, v230, v231
	v_cvt_pk_bf16_f32 v231, v232, v233
	global_store_dwordx2 v[242:243], v[230:231], off offset:96
	v_add_co_u32_e32 v242, vcc, 0x8000, v242
	s_nop 1
	v_addc_co_u32_e32 v243, vcc, 0, v243, vcc
	global_load_dwordx4 v[218:221], v[244:245], off offset:0
	global_load_dwordx4 v[222:225], v[244:245], off offset:64
	global_load_dwordx4 v[226:229], v[244:245], off offset:128
	global_load_dwordx4 v[230:233], v[244:245], off offset:192
	v_add_co_u32_e32 v244, vcc, 0x10000, v244
	s_nop 1
	v_addc_co_u32_e32 v245, vcc, 0, v245, vcc
	s_waitcnt vmcnt(8)
	v_pk_add_f32 v[200:201], v[200:201], v[24:25]
	v_pk_add_f32 v[202:203], v[202:203], v[26:27]
	v_fmac_f32_e32 v252, v200, v200
	v_fmac_f32_e32 v252, v201, v201
	v_fmac_f32_e32 v252, v202, v202
	v_fmac_f32_e32 v252, v203, v203
	v_cvt_pk_bf16_f32 v200, v200, v201
	v_cvt_pk_bf16_f32 v201, v202, v203
	global_store_dwordx2 v[242:243], v[200:201], off offset:0
	v_pk_add_f32 v[204:205], v[204:205], v[56:57]
	v_pk_add_f32 v[206:207], v[206:207], v[58:59]
	v_fmac_f32_e32 v252, v204, v204
	v_fmac_f32_e32 v252, v205, v205
	v_fmac_f32_e32 v252, v206, v206
	v_fmac_f32_e32 v252, v207, v207
	v_cvt_pk_bf16_f32 v204, v204, v205
	v_cvt_pk_bf16_f32 v205, v206, v207
	global_store_dwordx2 v[242:243], v[204:205], off offset:32
	v_pk_add_f32 v[210:211], v[210:211], v[88:89]
	v_pk_add_f32 v[212:213], v[212:213], v[90:91]
	v_fmac_f32_e32 v252, v210, v210
	v_fmac_f32_e32 v252, v211, v211
	v_fmac_f32_e32 v252, v212, v212
	v_fmac_f32_e32 v252, v213, v213
	v_cvt_pk_bf16_f32 v210, v210, v211
	v_cvt_pk_bf16_f32 v211, v212, v213
	global_store_dwordx2 v[242:243], v[210:211], off offset:64
	v_pk_add_f32 v[214:215], v[214:215], v[120:121]
	v_pk_add_f32 v[216:217], v[216:217], v[122:123]
	v_fmac_f32_e32 v252, v214, v214
	v_fmac_f32_e32 v252, v215, v215
	v_fmac_f32_e32 v252, v216, v216
	v_fmac_f32_e32 v252, v217, v217
	v_cvt_pk_bf16_f32 v214, v214, v215
	v_cvt_pk_bf16_f32 v215, v216, v217
	global_store_dwordx2 v[242:243], v[214:215], off offset:96
	v_add_co_u32_e32 v242, vcc, 0x8000, v242
	s_nop 1
	v_addc_co_u32_e32 v243, vcc, 0, v243, vcc
	s_waitcnt vmcnt(4)
	v_pk_add_f32 v[218:219], v[218:219], v[28:29]
	v_pk_add_f32 v[220:221], v[220:221], v[30:31]
	v_fmac_f32_e32 v253, v218, v218
	v_fmac_f32_e32 v253, v219, v219
	v_fmac_f32_e32 v253, v220, v220
	v_fmac_f32_e32 v253, v221, v221
	v_cvt_pk_bf16_f32 v218, v218, v219
	v_cvt_pk_bf16_f32 v219, v220, v221
	global_store_dwordx2 v[242:243], v[218:219], off offset:0
	v_pk_add_f32 v[222:223], v[222:223], v[60:61]
	v_pk_add_f32 v[224:225], v[224:225], v[62:63]
	v_fmac_f32_e32 v253, v222, v222
	v_fmac_f32_e32 v253, v223, v223
	v_fmac_f32_e32 v253, v224, v224
	v_fmac_f32_e32 v253, v225, v225
	v_cvt_pk_bf16_f32 v222, v222, v223
	v_cvt_pk_bf16_f32 v223, v224, v225
	global_store_dwordx2 v[242:243], v[222:223], off offset:32
	v_pk_add_f32 v[226:227], v[226:227], v[92:93]
	v_pk_add_f32 v[228:229], v[228:229], v[94:95]
	v_fmac_f32_e32 v253, v226, v226
	v_fmac_f32_e32 v253, v227, v227
	v_fmac_f32_e32 v253, v228, v228
	v_fmac_f32_e32 v253, v229, v229
	v_cvt_pk_bf16_f32 v226, v226, v227
	v_cvt_pk_bf16_f32 v227, v228, v229
	global_store_dwordx2 v[242:243], v[226:227], off offset:64
	v_pk_add_f32 v[230:231], v[230:231], v[124:125]
	v_pk_add_f32 v[232:233], v[232:233], v[126:127]
	v_fmac_f32_e32 v253, v230, v230
	v_fmac_f32_e32 v253, v231, v231
	v_fmac_f32_e32 v253, v232, v232
	v_fmac_f32_e32 v253, v233, v233
	v_cvt_pk_bf16_f32 v230, v230, v231
	v_cvt_pk_bf16_f32 v231, v232, v233
	global_store_dwordx2 v[242:243], v[230:231], off offset:96
	v_add_co_u32_e32 v242, vcc, 0x8000, v242
	s_nop 1
	v_addc_co_u32_e32 v243, vcc, 0, v243, vcc
	v_and_b32_e32 v200, 63, v208
	v_and_b32_e32 v205, 15, v200
	v_lshrrev_b32_e32 v206, 4, v200
	v_and_b32_e32 v207, 7, v205
	v_xor_b32_e32 v207, v207, v206
	v_lshlrev_b32_e32 v207, 4, v207
	v_lshl_add_u32 v242, v205, 7, v207
	v_xor_b32_e32 v243, 64, v242
	s_add_i32 s21, s21, 1
	s_cmp_lt_u32 s21, 4
	s_cbranch_scc1 .Lg2_chunk
	s_waitcnt vmcnt(0)
	v_and_b32_e32 v200, 63, v208
	v_xor_b32_e32 v201, 16, v200
	v_lshlrev_b32_e32 v201, 2, v201
	v_xor_b32_e32 v202, 32, v200
	v_lshlrev_b32_e32 v202, 2, v202
	v_and_b32_e32 v203, 15, v200
	v_lshlrev_b32_e32 v203, 2, v203
	v_add_u32_e32 v203, 0x12400, v203
	ds_bpermute_b32 v204, v201, v246
	s_waitcnt lgkmcnt(0)
	v_add_f32_e32 v246, v246, v204
	ds_bpermute_b32 v204, v202, v246
	s_waitcnt lgkmcnt(0)
	v_add_f32_e32 v246, v246, v204
	ds_bpermute_b32 v204, v201, v247
	s_waitcnt lgkmcnt(0)
	v_add_f32_e32 v247, v247, v204
	ds_bpermute_b32 v204, v202, v247
	s_waitcnt lgkmcnt(0)
	v_add_f32_e32 v247, v247, v204
	ds_bpermute_b32 v204, v201, v248
	s_waitcnt lgkmcnt(0)
	v_add_f32_e32 v248, v248, v204
	ds_bpermute_b32 v204, v202, v248
	s_waitcnt lgkmcnt(0)
	v_add_f32_e32 v248, v248, v204
	ds_bpermute_b32 v204, v201, v249
	s_waitcnt lgkmcnt(0)
	v_add_f32_e32 v249, v249, v204
	ds_bpermute_b32 v204, v202, v249
	s_waitcnt lgkmcnt(0)
	v_add_f32_e32 v249, v249, v204
	ds_bpermute_b32 v204, v201, v250
	s_waitcnt lgkmcnt(0)
	v_add_f32_e32 v250, v250, v204
	ds_bpermute_b32 v204, v202, v250
	s_waitcnt lgkmcnt(0)
	v_add_f32_e32 v250, v250, v204
	ds_bpermute_b32 v204, v201, v251
	s_waitcnt lgkmcnt(0)
	v_add_f32_e32 v251, v251, v204
	ds_bpermute_b32 v204, v202, v251
	s_waitcnt lgkmcnt(0)
	v_add_f32_e32 v251, v251, v204
	ds_bpermute_b32 v204, v201, v252
	s_waitcnt lgkmcnt(0)
	v_add_f32_e32 v252, v252, v204
	ds_bpermute_b32 v204, v202, v252
	s_waitcnt lgkmcnt(0)
	v_add_f32_e32 v252, v252, v204
	ds_bpermute_b32 v204, v201, v253
	s_waitcnt lgkmcnt(0)
	v_add_f32_e32 v253, v253, v204
	ds_bpermute_b32 v204, v202, v253
	s_waitcnt lgkmcnt(0)
	v_add_f32_e32 v253, v253, v204
	s_mov_b64 s[24:25], exec
	s_mov_b64 exec, 0xffff
	ds_add_f32 v203, v246 offset:0
	ds_add_f32 v203, v247 offset:64
	ds_add_f32 v203, v248 offset:128
	ds_add_f32 v203, v249 offset:192
	ds_add_f32 v203, v250 offset:256
	ds_add_f32 v203, v251 offset:320
	ds_add_f32 v203, v252 offset:384
	ds_add_f32 v203, v253 offset:448
	s_mov_b64 exec, s[24:25]


.Lg3_nda1:
.Lg3_sada1:
	v_add_u32_e32 v244, s16, v242
	v_add_u32_e32 v245, s16, v243
	ds_read_b128 v[198:201], v244 offset:0
	ds_read_b128 v[202:205], v244 offset:2048
	ds_read_b128 v[210:213], v244 offset:4096
	ds_read_b128 v[214:217], v244 offset:6144
	ds_read_b128 v[218:221], v244 offset:8192
	ds_read_b128 v[222:225], v244 offset:10240
	ds_read_b128 v[226:229], v244 offset:12288
	ds_read_b128 v[230:233], v244 offset:14336
	s_waitcnt lgkmcnt(4)
	v_mfma_f32_16x16x32_bf16 v[0:3], v[128:131], v[198:201], v[0:3]
	v_mfma_f32_16x16x32_bf16 v[32:35], v[132:135], v[198:201], v[32:35]
	v_mfma_f32_16x16x32_bf16 v[64:67], v[136:139], v[198:201], v[64:67]
	v_mfma_f32_16x16x32_bf16 v[96:99], v[140:143], v[198:201], v[96:99]
	v_mfma_f32_16x16x32_bf16 v[4:7], v[128:131], v[202:205], v[4:7]
	v_mfma_f32_16x16x32_bf16 v[36:39], v[132:135], v[202:205], v[36:39]
	v_mfma_f32_16x16x32_bf16 v[68:71], v[136:139], v[202:205], v[68:71]
	v_mfma_f32_16x16x32_bf16 v[100:103], v[140:143], v[202:205], v[100:103]
	v_mfma_f32_16x16x32_bf16 v[8:11], v[128:131], v[210:213], v[8:11]
	v_mfma_f32_16x16x32_bf16 v[40:43], v[132:135], v[210:213], v[40:43]
	v_mfma_f32_16x16x32_bf16 v[72:75], v[136:139], v[210:213], v[72:75]
	v_mfma_f32_16x16x32_bf16 v[104:107], v[140:143], v[210:213], v[104:107]
	v_mfma_f32_16x16x32_bf16 v[12:15], v[128:131], v[214:217], v[12:15]
	v_mfma_f32_16x16x32_bf16 v[44:47], v[132:135], v[214:217], v[44:47]
	v_mfma_f32_16x16x32_bf16 v[76:79], v[136:139], v[214:217], v[76:79]
	v_mfma_f32_16x16x32_bf16 v[108:111], v[140:143], v[214:217], v[108:111]
	ds_read_b128 v[198:201], v245 offset:0
	ds_read_b128 v[202:205], v245 offset:2048
	ds_read_b128 v[210:213], v245 offset:4096
	ds_read_b128 v[214:217], v245 offset:6144
	s_waitcnt lgkmcnt(4)
	v_mfma_f32_16x16x32_bf16 v[16:19], v[128:131], v[218:221], v[16:19]
	v_mfma_f32_16x16x32_bf16 v[48:51], v[132:135], v[218:221], v[48:51]
	v_mfma_f32_16x16x32_bf16 v[80:83], v[136:139], v[218:221], v[80:83]
	v_mfma_f32_16x16x32_bf16 v[112:115], v[140:143], v[218:221], v[112:115]
	v_mfma_f32_16x16x32_bf16 v[20:23], v[128:131], v[222:225], v[20:23]
	v_mfma_f32_16x16x32_bf16 v[52:55], v[132:135], v[222:225], v[52:55]
	v_mfma_f32_16x16x32_bf16 v[84:87], v[136:139], v[222:225], v[84:87]
	v_mfma_f32_16x16x32_bf16 v[116:119], v[140:143], v[222:225], v[116:119]
	v_mfma_f32_16x16x32_bf16 v[24:27], v[128:131], v[226:229], v[24:27]
	v_mfma_f32_16x16x32_bf16 v[56:59], v[132:135], v[226:229], v[56:59]
	v_mfma_f32_16x16x32_bf16 v[88:91], v[136:139], v[226:229], v[88:91]
	v_mfma_f32_16x16x32_bf16 v[120:123], v[140:143], v[226:229], v[120:123]
	v_mfma_f32_16x16x32_bf16 v[28:31], v[128:131], v[230:233], v[28:31]
	v_mfma_f32_16x16x32_bf16 v[60:63], v[132:135], v[230:233], v[60:63]
	v_mfma_f32_16x16x32_bf16 v[92:95], v[136:139], v[230:233], v[92:95]
	v_mfma_f32_16x16x32_bf16 v[124:127], v[140:143], v[230:233], v[124:127]
	ds_read_b128 v[218:221], v245 offset:8192
	ds_read_b128 v[222:225], v245 offset:10240
	ds_read_b128 v[226:229], v245 offset:12288
	ds_read_b128 v[230:233], v245 offset:14336
	s_waitcnt vmcnt(16)
	global_load_dwordx4 v[128:131], v238, s[14:15]
	global_load_dwordx4 v[132:135], v239, s[14:15]
	global_load_dwordx4 v[136:139], v240, s[14:15]
	global_load_dwordx4 v[140:143], v241, s[14:15]
	s_cmp_eq_u32 s19, 31
	s_cbranch_scc1 .Lg3_sww2
	s_add_u32 s14, s14, 1024
	s_addc_u32 s15, s15, 0
	s_branch .Lg3_swdw2

.Lg3_wndw2:
.Lg3_swdw2:
	s_add_i32 s19, s19, 1
	s_waitcnt lgkmcnt(4)
	v_mfma_f32_16x16x32_bf16 v[0:3], v[144:147], v[198:201], v[0:3]
	v_mfma_f32_16x16x32_bf16 v[32:35], v[148:151], v[198:201], v[32:35]
	v_mfma_f32_16x16x32_bf16 v[64:67], v[152:155], v[198:201], v[64:67]
	v_mfma_f32_16x16x32_bf16 v[96:99], v[156:159], v[198:201], v[96:99]
	v_mfma_f32_16x16x32_bf16 v[4:7], v[144:147], v[202:205], v[4:7]
	v_mfma_f32_16x16x32_bf16 v[36:39], v[148:151], v[202:205], v[36:39]
	v_mfma_f32_16x16x32_bf16 v[68:71], v[152:155], v[202:205], v[68:71]
	v_mfma_f32_16x16x32_bf16 v[100:103], v[156:159], v[202:205], v[100:103]
	v_mfma_f32_16x16x32_bf16 v[8:11], v[144:147], v[210:213], v[8:11]
	v_mfma_f32_16x16x32_bf16 v[40:43], v[148:151], v[210:213], v[40:43]
	v_mfma_f32_16x16x32_bf16 v[72:75], v[152:155], v[210:213], v[72:75]
	v_mfma_f32_16x16x32_bf16 v[104:107], v[156:159], v[210:213], v[104:107]
	v_mfma_f32_16x16x32_bf16 v[12:15], v[144:147], v[214:217], v[12:15]
	v_mfma_f32_16x16x32_bf16 v[44:47], v[148:151], v[214:217], v[44:47]
	v_mfma_f32_16x16x32_bf16 v[76:79], v[152:155], v[214:217], v[76:79]
	v_mfma_f32_16x16x32_bf16 v[108:111], v[156:159], v[214:217], v[108:111]
	s_waitcnt lgkmcnt(0)
	v_mfma_f32_16x16x32_bf16 v[16:19], v[144:147], v[218:221], v[16:19]
	v_mfma_f32_16x16x32_bf16 v[48:51], v[148:151], v[218:221], v[48:51]
	v_mfma_f32_16x16x32_bf16 v[80:83], v[152:155], v[218:221], v[80:83]
	v_mfma_f32_16x16x32_bf16 v[112:115], v[156:159], v[218:221], v[112:115]
	v_mfma_f32_16x16x32_bf16 v[20:23], v[144:147], v[222:225], v[20:23]
	v_mfma_f32_16x16x32_bf16 v[52:55], v[148:151], v[222:225], v[52:55]
	v_mfma_f32_16x16x32_bf16 v[84:87], v[152:155], v[222:225], v[84:87]
	v_mfma_f32_16x16x32_bf16 v[116:119], v[156:159], v[222:225], v[116:119]
	v_mfma_f32_16x16x32_bf16 v[24:27], v[144:147], v[226:229], v[24:27]
	v_mfma_f32_16x16x32_bf16 v[56:59], v[148:151], v[226:229], v[56:59]
	v_mfma_f32_16x16x32_bf16 v[88:91], v[152:155], v[226:229], v[88:91]
	v_mfma_f32_16x16x32_bf16 v[120:123], v[156:159], v[226:229], v[120:123]
	v_mfma_f32_16x16x32_bf16 v[28:31], v[144:147], v[230:233], v[28:31]
	v_mfma_f32_16x16x32_bf16 v[60:63], v[148:151], v[230:233], v[60:63]
	v_mfma_f32_16x16x32_bf16 v[92:95], v[152:155], v[230:233], v[92:95]
	v_mfma_f32_16x16x32_bf16 v[124:127], v[156:159], v[230:233], v[124:127]
	s_add_i32 s16, s16, 0x4000
	s_cmp_lt_u32 s16, 0xc000
	s_cselect_b32 s16, s16, 0
	s_add_i32 s17, s17, 0x4000
	s_cmp_lt_u32 s17, 0xc000
	s_cselect_b32 s17, s17, 0
	s_add_i32 s18, s18, 1
	s_waitcnt vmcnt(12)
	s_barrier
	global_load_dwordx4 v[144:147], v238, s[14:15]
	global_load_dwordx4 v[148:151], v239, s[14:15]
	global_load_dwordx4 v[152:155], v240, s[14:15]
	global_load_dwordx4 v[156:159], v241, s[14:15]
	s_cmp_eq_u32 s19, 31
	s_cbranch_scc1 .Lg3_sww3
	s_add_u32 s14, s14, 1024
	s_addc_u32 s15, s15, 0
	s_branch .Lg3_swdw3

.Lg3_nda4:
.Lg3_sada4:
	v_add_u32_e32 v244, s16, v242
	v_add_u32_e32 v245, s16, v243
	ds_read_b128 v[198:201], v244 offset:0
	ds_read_b128 v[202:205], v244 offset:2048
	ds_read_b128 v[210:213], v244 offset:4096
	ds_read_b128 v[214:217], v244 offset:6144
	ds_read_b128 v[218:221], v244 offset:8192
	ds_read_b128 v[222:225], v244 offset:10240
	ds_read_b128 v[226:229], v244 offset:12288
	ds_read_b128 v[230:233], v244 offset:14336
	s_waitcnt lgkmcnt(4)
	v_mfma_f32_16x16x32_bf16 v[0:3], v[160:163], v[198:201], v[0:3]
	v_mfma_f32_16x16x32_bf16 v[32:35], v[164:167], v[198:201], v[32:35]
	v_mfma_f32_16x16x32_bf16 v[64:67], v[168:171], v[198:201], v[64:67]
	v_mfma_f32_16x16x32_bf16 v[96:99], v[172:175], v[198:201], v[96:99]
	v_mfma_f32_16x16x32_bf16 v[4:7], v[160:163], v[202:205], v[4:7]
	v_mfma_f32_16x16x32_bf16 v[36:39], v[164:167], v[202:205], v[36:39]
	v_mfma_f32_16x16x32_bf16 v[68:71], v[168:171], v[202:205], v[68:71]
	v_mfma_f32_16x16x32_bf16 v[100:103], v[172:175], v[202:205], v[100:103]
	v_mfma_f32_16x16x32_bf16 v[8:11], v[160:163], v[210:213], v[8:11]
	v_mfma_f32_16x16x32_bf16 v[40:43], v[164:167], v[210:213], v[40:43]
	v_mfma_f32_16x16x32_bf16 v[72:75], v[168:171], v[210:213], v[72:75]
	v_mfma_f32_16x16x32_bf16 v[104:107], v[172:175], v[210:213], v[104:107]
	v_mfma_f32_16x16x32_bf16 v[12:15], v[160:163], v[214:217], v[12:15]
	v_mfma_f32_16x16x32_bf16 v[44:47], v[164:167], v[214:217], v[44:47]
	v_mfma_f32_16x16x32_bf16 v[76:79], v[168:171], v[214:217], v[76:79]
	v_mfma_f32_16x16x32_bf16 v[108:111], v[172:175], v[214:217], v[108:111]
	ds_read_b128 v[198:201], v245 offset:0
	ds_read_b128 v[202:205], v245 offset:2048
	ds_read_b128 v[210:213], v245 offset:4096
	ds_read_b128 v[214:217], v245 offset:6144
	s_waitcnt lgkmcnt(4)
	v_mfma_f32_16x16x32_bf16 v[16:19], v[160:163], v[218:221], v[16:19]
	v_mfma_f32_16x16x32_bf16 v[48:51], v[164:167], v[218:221], v[48:51]
	v_mfma_f32_16x16x32_bf16 v[80:83], v[168:171], v[218:221], v[80:83]
	v_mfma_f32_16x16x32_bf16 v[112:115], v[172:175], v[218:221], v[112:115]
	v_mfma_f32_16x16x32_bf16 v[20:23], v[160:163], v[222:225], v[20:23]
	v_mfma_f32_16x16x32_bf16 v[52:55], v[164:167], v[222:225], v[52:55]
	v_mfma_f32_16x16x32_bf16 v[84:87], v[168:171], v[222:225], v[84:87]
	v_mfma_f32_16x16x32_bf16 v[116:119], v[172:175], v[222:225], v[116:119]
	v_mfma_f32_16x16x32_bf16 v[24:27], v[160:163], v[226:229], v[24:27]
	v_mfma_f32_16x16x32_bf16 v[56:59], v[164:167], v[226:229], v[56:59]
	v_mfma_f32_16x16x32_bf16 v[88:91], v[168:171], v[226:229], v[88:91]
	v_mfma_f32_16x16x32_bf16 v[120:123], v[172:175], v[226:229], v[120:123]
	v_mfma_f32_16x16x32_bf16 v[28:31], v[160:163], v[230:233], v[28:31]
	v_mfma_f32_16x16x32_bf16 v[60:63], v[164:167], v[230:233], v[60:63]
	v_mfma_f32_16x16x32_bf16 v[92:95], v[168:171], v[230:233], v[92:95]
	v_mfma_f32_16x16x32_bf16 v[124:127], v[172:175], v[230:233], v[124:127]
	ds_read_b128 v[218:221], v245 offset:8192
	ds_read_b128 v[222:225], v245 offset:10240
	ds_read_b128 v[226:229], v245 offset:12288
	ds_read_b128 v[230:233], v245 offset:14336
	s_waitcnt vmcnt(16)
	global_load_dwordx4 v[160:163], v238, s[14:15]
	global_load_dwordx4 v[164:167], v239, s[14:15]
	global_load_dwordx4 v[168:171], v240, s[14:15]
	global_load_dwordx4 v[172:175], v241, s[14:15]
	s_cmp_eq_u32 s19, 31
	s_cbranch_scc1 .Lg3_sww5
	s_add_u32 s14, s14, 1024
	s_addc_u32 s15, s15, 0
	s_branch .Lg3_swdw5

.Lg3_wndw5:
.Lg3_swdw5:
	s_add_i32 s19, s19, 1
	s_waitcnt lgkmcnt(4)
	v_mfma_f32_16x16x32_bf16 v[0:3], v[176:179], v[198:201], v[0:3]
	v_mfma_f32_16x16x32_bf16 v[32:35], v[182:185], v[198:201], v[32:35]
	v_mfma_f32_16x16x32_bf16 v[64:67], v[186:189], v[198:201], v[64:67]
	v_mfma_f32_16x16x32_bf16 v[96:99], v[194:197], v[198:201], v[96:99]
	v_mfma_f32_16x16x32_bf16 v[4:7], v[176:179], v[202:205], v[4:7]
	v_mfma_f32_16x16x32_bf16 v[36:39], v[182:185], v[202:205], v[36:39]
	v_mfma_f32_16x16x32_bf16 v[68:71], v[186:189], v[202:205], v[68:71]
	v_mfma_f32_16x16x32_bf16 v[100:103], v[194:197], v[202:205], v[100:103]
	v_mfma_f32_16x16x32_bf16 v[8:11], v[176:179], v[210:213], v[8:11]
	v_mfma_f32_16x16x32_bf16 v[40:43], v[182:185], v[210:213], v[40:43]
	v_mfma_f32_16x16x32_bf16 v[72:75], v[186:189], v[210:213], v[72:75]
	v_mfma_f32_16x16x32_bf16 v[104:107], v[194:197], v[210:213], v[104:107]
	v_mfma_f32_16x16x32_bf16 v[12:15], v[176:179], v[214:217], v[12:15]
	v_mfma_f32_16x16x32_bf16 v[44:47], v[182:185], v[214:217], v[44:47]
	v_mfma_f32_16x16x32_bf16 v[76:79], v[186:189], v[214:217], v[76:79]
	v_mfma_f32_16x16x32_bf16 v[108:111], v[194:197], v[214:217], v[108:111]
	s_waitcnt lgkmcnt(0)
	v_mfma_f32_16x16x32_bf16 v[16:19], v[176:179], v[218:221], v[16:19]
	v_mfma_f32_16x16x32_bf16 v[48:51], v[182:185], v[218:221], v[48:51]
	v_mfma_f32_16x16x32_bf16 v[80:83], v[186:189], v[218:221], v[80:83]
	v_mfma_f32_16x16x32_bf16 v[112:115], v[194:197], v[218:221], v[112:115]
	v_mfma_f32_16x16x32_bf16 v[20:23], v[176:179], v[222:225], v[20:23]
	v_mfma_f32_16x16x32_bf16 v[52:55], v[182:185], v[222:225], v[52:55]
	v_mfma_f32_16x16x32_bf16 v[84:87], v[186:189], v[222:225], v[84:87]
	v_mfma_f32_16x16x32_bf16 v[116:119], v[194:197], v[222:225], v[116:119]
	v_mfma_f32_16x16x32_bf16 v[24:27], v[176:179], v[226:229], v[24:27]
	v_mfma_f32_16x16x32_bf16 v[56:59], v[182:185], v[226:229], v[56:59]
	v_mfma_f32_16x16x32_bf16 v[88:91], v[186:189], v[226:229], v[88:91]
	v_mfma_f32_16x16x32_bf16 v[120:123], v[194:197], v[226:229], v[120:123]
	v_mfma_f32_16x16x32_bf16 v[28:31], v[176:179], v[230:233], v[28:31]
	v_mfma_f32_16x16x32_bf16 v[60:63], v[182:185], v[230:233], v[60:63]
	v_mfma_f32_16x16x32_bf16 v[92:95], v[186:189], v[230:233], v[92:95]
	v_mfma_f32_16x16x32_bf16 v[124:127], v[194:197], v[230:233], v[124:127]
	s_add_i32 s16, s16, 0x4000
	s_cmp_lt_u32 s16, 0xc000
	s_cselect_b32 s16, s16, 0
	s_add_i32 s17, s17, 0x4000
	s_cmp_lt_u32 s17, 0xc000
	s_cselect_b32 s17, s17, 0
	s_add_i32 s18, s18, 1
	s_cmp_lt_u32 s18, 16
	s_cbranch_scc1 .Lg3_loop
	s_nop 7
	s_nop 7
	v_and_b32_e32 v198, 63, v208
	v_lshrrev_b32_e32 v199, 6, v208
	v_and_b32_e32 v200, 15, v198
	v_lshrrev_b32_e32 v201, 4, v198
	s_add_i32 s21, s11, s10
	s_and_b32 s21, s21, 3
	s_lshl_b32 s21, s21, 9
	s_lshl_b32 s2, s10, 18
	s_add_i32 s2, s2, s21
	s_add_i32 s2, s2, 0x26000000
	v_lshlrev_b32_e32 v244, 11, v200
	v_lshl_add_u32 v244, v199, 7, v244
	v_lshl_add_u32 v244, v201, 3, v244
	v_add_u32_e32 v244, s2, v244
	v_mov_b32_e32 v245, s93
	v_add_co_u32_e32 v244, vcc, s92, v244
	s_nop 1
	v_addc_co_u32_e32 v245, vcc, 0, v245, vcc
	v_mul_f32_e32 v0, v246, v0
	v_mul_f32_e32 v1, v246, v1
	v_mul_f32_e32 v2, v246, v2
	v_mul_f32_e32 v3, v246, v3
	v_cvt_pk_bf16_f32 v202, v0, v1
	v_cvt_pk_bf16_f32 v203, v2, v3
	global_store_dwordx2 v[244:245], v[202:203], off offset:0
	v_mul_f32_e32 v32, v246, v32
	v_mul_f32_e32 v33, v246, v33
	v_mul_f32_e32 v34, v246, v34
	v_mul_f32_e32 v35, v246, v35
	v_cvt_pk_bf16_f32 v204, v32, v33
	v_cvt_pk_bf16_f32 v205, v34, v35
	global_store_dwordx2 v[244:245], v[204:205], off offset:32
	v_mul_f32_e32 v64, v246, v64
	v_mul_f32_e32 v65, v246, v65
	v_mul_f32_e32 v66, v246, v66
	v_mul_f32_e32 v67, v246, v67
	v_cvt_pk_bf16_f32 v210, v64, v65
	v_cvt_pk_bf16_f32 v211, v66, v67
	global_store_dwordx2 v[244:245], v[210:211], off offset:64
	v_mul_f32_e32 v96, v246, v96
	v_mul_f32_e32 v97, v246, v97
	v_mul_f32_e32 v98, v246, v98
	v_mul_f32_e32 v99, v246, v99
	v_cvt_pk_bf16_f32 v212, v96, v97
	v_cvt_pk_bf16_f32 v213, v98, v99
	global_store_dwordx2 v[244:245], v[212:213], off offset:96
	v_add_co_u32_e32 v244, vcc, 0x8000, v244
	s_nop 1
	v_addc_co_u32_e32 v245, vcc, 0, v245, vcc
	v_mul_f32_e32 v4, v247, v4
	v_mul_f32_e32 v5, v247, v5
	v_mul_f32_e32 v6, v247, v6
	v_mul_f32_e32 v7, v247, v7
	v_cvt_pk_bf16_f32 v202, v4, v5
	v_cvt_pk_bf16_f32 v203, v6, v7
	global_store_dwordx2 v[244:245], v[202:203], off offset:0
	v_mul_f32_e32 v36, v247, v36
	v_mul_f32_e32 v37, v247, v37
	v_mul_f32_e32 v38, v247, v38
	v_mul_f32_e32 v39, v247, v39
	v_cvt_pk_bf16_f32 v204, v36, v37
	v_cvt_pk_bf16_f32 v205, v38, v39
	global_store_dwordx2 v[244:245], v[204:205], off offset:32
	v_mul_f32_e32 v68, v247, v68
	v_mul_f32_e32 v69, v247, v69
	v_mul_f32_e32 v70, v247, v70
	v_mul_f32_e32 v71, v247, v71
	v_cvt_pk_bf16_f32 v210, v68, v69
	v_cvt_pk_bf16_f32 v211, v70, v71
	global_store_dwordx2 v[244:245], v[210:211], off offset:64
	v_mul_f32_e32 v100, v247, v100
	v_mul_f32_e32 v101, v247, v101
	v_mul_f32_e32 v102, v247, v102
	v_mul_f32_e32 v103, v247, v103
	v_cvt_pk_bf16_f32 v212, v100, v101
	v_cvt_pk_bf16_f32 v213, v102, v103
	global_store_dwordx2 v[244:245], v[212:213], off offset:96
	v_add_co_u32_e32 v244, vcc, 0x8000, v244
	s_nop 1
	v_addc_co_u32_e32 v245, vcc, 0, v245, vcc
	v_mul_f32_e32 v8, v248, v8
	v_mul_f32_e32 v9, v248, v9
	v_mul_f32_e32 v10, v248, v10
	v_mul_f32_e32 v11, v248, v11
	v_cvt_pk_bf16_f32 v202, v8, v9
	v_cvt_pk_bf16_f32 v203, v10, v11
	global_store_dwordx2 v[244:245], v[202:203], off offset:0
	v_mul_f32_e32 v40, v248, v40
	v_mul_f32_e32 v41, v248, v41
	v_mul_f32_e32 v42, v248, v42
	v_mul_f32_e32 v43, v248, v43
	v_cvt_pk_bf16_f32 v204, v40, v41
	v_cvt_pk_bf16_f32 v205, v42, v43
	global_store_dwordx2 v[244:245], v[204:205], off offset:32
	v_mul_f32_e32 v72, v248, v72
	v_mul_f32_e32 v73, v248, v73
	v_mul_f32_e32 v74, v248, v74
	v_mul_f32_e32 v75, v248, v75
	v_cvt_pk_bf16_f32 v210, v72, v73
	v_cvt_pk_bf16_f32 v211, v74, v75
	global_store_dwordx2 v[244:245], v[210:211], off offset:64
	v_mul_f32_e32 v104, v248, v104
	v_mul_f32_e32 v105, v248, v105
	v_mul_f32_e32 v106, v248, v106
	v_mul_f32_e32 v107, v248, v107
	v_cvt_pk_bf16_f32 v212, v104, v105
	v_cvt_pk_bf16_f32 v213, v106, v107
	global_store_dwordx2 v[244:245], v[212:213], off offset:96
	v_add_co_u32_e32 v244, vcc, 0x8000, v244
	s_nop 1
	v_addc_co_u32_e32 v245, vcc, 0, v245, vcc
	v_mul_f32_e32 v12, v249, v12
	v_mul_f32_e32 v13, v249, v13
	v_mul_f32_e32 v14, v249, v14
	v_mul_f32_e32 v15, v249, v15
	v_cvt_pk_bf16_f32 v202, v12, v13
	v_cvt_pk_bf16_f32 v203, v14, v15
	global_store_dwordx2 v[244:245], v[202:203], off offset:0
	v_mul_f32_e32 v44, v249, v44
	v_mul_f32_e32 v45, v249, v45
	v_mul_f32_e32 v46, v249, v46
	v_mul_f32_e32 v47, v249, v47
	v_cvt_pk_bf16_f32 v204, v44, v45
	v_cvt_pk_bf16_f32 v205, v46, v47
	global_store_dwordx2 v[244:245], v[204:205], off offset:32
	v_mul_f32_e32 v76, v249, v76
	v_mul_f32_e32 v77, v249, v77
	v_mul_f32_e32 v78, v249, v78
	v_mul_f32_e32 v79, v249, v79
	v_cvt_pk_bf16_f32 v210, v76, v77
	v_cvt_pk_bf16_f32 v211, v78, v79
	global_store_dwordx2 v[244:245], v[210:211], off offset:64
	v_mul_f32_e32 v108, v249, v108
	v_mul_f32_e32 v109, v249, v109
	v_mul_f32_e32 v110, v249, v110
	v_mul_f32_e32 v111, v249, v111
	v_cvt_pk_bf16_f32 v212, v108, v109
	v_cvt_pk_bf16_f32 v213, v110, v111
	global_store_dwordx2 v[244:245], v[212:213], off offset:96
	v_add_co_u32_e32 v244, vcc, 0x8000, v244
	s_nop 1
	v_addc_co_u32_e32 v245, vcc, 0, v245, vcc
	v_mul_f32_e32 v16, v250, v16
	v_mul_f32_e32 v17, v250, v17
	v_mul_f32_e32 v18, v250, v18
	v_mul_f32_e32 v19, v250, v19
	v_cvt_pk_bf16_f32 v202, v16, v17
	v_cvt_pk_bf16_f32 v203, v18, v19
	global_store_dwordx2 v[244:245], v[202:203], off offset:0
	v_mul_f32_e32 v48, v250, v48
	v_mul_f32_e32 v49, v250, v49
	v_mul_f32_e32 v50, v250, v50
	v_mul_f32_e32 v51, v250, v51
	v_cvt_pk_bf16_f32 v204, v48, v49
	v_cvt_pk_bf16_f32 v205, v50, v51
	global_store_dwordx2 v[244:245], v[204:205], off offset:32
	v_mul_f32_e32 v80, v250, v80
	v_mul_f32_e32 v81, v250, v81
	v_mul_f32_e32 v82, v250, v82
	v_mul_f32_e32 v83, v250, v83
	v_cvt_pk_bf16_f32 v210, v80, v81
	v_cvt_pk_bf16_f32 v211, v82, v83
	global_store_dwordx2 v[244:245], v[210:211], off offset:64
	v_mul_f32_e32 v112, v250, v112
	v_mul_f32_e32 v113, v250, v113
	v_mul_f32_e32 v114, v250, v114
	v_mul_f32_e32 v115, v250, v115
	v_cvt_pk_bf16_f32 v212, v112, v113
	v_cvt_pk_bf16_f32 v213, v114, v115
	global_store_dwordx2 v[244:245], v[212:213], off offset:96
	v_add_co_u32_e32 v244, vcc, 0x8000, v244
	s_nop 1
	v_addc_co_u32_e32 v245, vcc, 0, v245, vcc
	v_mul_f32_e32 v20, v251, v20
	v_mul_f32_e32 v21, v251, v21
	v_mul_f32_e32 v22, v251, v22
	v_mul_f32_e32 v23, v251, v23
	v_cvt_pk_bf16_f32 v202, v20, v21
	v_cvt_pk_bf16_f32 v203, v22, v23
	global_store_dwordx2 v[244:245], v[202:203], off offset:0
	v_mul_f32_e32 v52, v251, v52
	v_mul_f32_e32 v53, v251, v53
	v_mul_f32_e32 v54, v251, v54
	v_mul_f32_e32 v55, v251, v55
	v_cvt_pk_bf16_f32 v204, v52, v53
	v_cvt_pk_bf16_f32 v205, v54, v55
	global_store_dwordx2 v[244:245], v[204:205], off offset:32
	v_mul_f32_e32 v84, v251, v84
	v_mul_f32_e32 v85, v251, v85
	v_mul_f32_e32 v86, v251, v86
	v_mul_f32_e32 v87, v251, v87
	v_cvt_pk_bf16_f32 v210, v84, v85
	v_cvt_pk_bf16_f32 v211, v86, v87
	global_store_dwordx2 v[244:245], v[210:211], off offset:64
	v_mul_f32_e32 v116, v251, v116
	v_mul_f32_e32 v117, v251, v117
	v_mul_f32_e32 v118, v251, v118
	v_mul_f32_e32 v119, v251, v119
	v_cvt_pk_bf16_f32 v212, v116, v117
	v_cvt_pk_bf16_f32 v213, v118, v119
	global_store_dwordx2 v[244:245], v[212:213], off offset:96
	v_add_co_u32_e32 v244, vcc, 0x8000, v244
	s_nop 1
	v_addc_co_u32_e32 v245, vcc, 0, v245, vcc
	v_mul_f32_e32 v24, v252, v24
	v_mul_f32_e32 v25, v252, v25
	v_mul_f32_e32 v26, v252, v26
	v_mul_f32_e32 v27, v252, v27
	v_cvt_pk_bf16_f32 v202, v24, v25
	v_cvt_pk_bf16_f32 v203, v26, v27
	global_store_dwordx2 v[244:245], v[202:203], off offset:0
	v_mul_f32_e32 v56, v252, v56
	v_mul_f32_e32 v57, v252, v57
	v_mul_f32_e32 v58, v252, v58
	v_mul_f32_e32 v59, v252, v59
	v_cvt_pk_bf16_f32 v204, v56, v57
	v_cvt_pk_bf16_f32 v205, v58, v59
	global_store_dwordx2 v[244:245], v[204:205], off offset:32
	v_mul_f32_e32 v88, v252, v88
	v_mul_f32_e32 v89, v252, v89
	v_mul_f32_e32 v90, v252, v90
	v_mul_f32_e32 v91, v252, v91
	v_cvt_pk_bf16_f32 v210, v88, v89
	v_cvt_pk_bf16_f32 v211, v90, v91
	global_store_dwordx2 v[244:245], v[210:211], off offset:64
	v_mul_f32_e32 v120, v252, v120
	v_mul_f32_e32 v121, v252, v121
	v_mul_f32_e32 v122, v252, v122
	v_mul_f32_e32 v123, v252, v123
	v_cvt_pk_bf16_f32 v212, v120, v121
	v_cvt_pk_bf16_f32 v213, v122, v123
	global_store_dwordx2 v[244:245], v[212:213], off offset:96
	v_add_co_u32_e32 v244, vcc, 0x8000, v244
	s_nop 1
	v_addc_co_u32_e32 v245, vcc, 0, v245, vcc
	v_mul_f32_e32 v28, v253, v28
	v_mul_f32_e32 v29, v253, v29
	v_mul_f32_e32 v30, v253, v30
	v_mul_f32_e32 v31, v253, v31
	v_cvt_pk_bf16_f32 v202, v28, v29
	v_cvt_pk_bf16_f32 v203, v30, v31
	global_store_dwordx2 v[244:245], v[202:203], off offset:0
	v_mul_f32_e32 v60, v253, v60
	v_mul_f32_e32 v61, v253, v61
	v_mul_f32_e32 v62, v253, v62
	v_mul_f32_e32 v63, v253, v63
	v_cvt_pk_bf16_f32 v204, v60, v61
	v_cvt_pk_bf16_f32 v205, v62, v63
	global_store_dwordx2 v[244:245], v[204:205], off offset:32
	v_mul_f32_e32 v92, v253, v92
	v_mul_f32_e32 v93, v253, v93
	v_mul_f32_e32 v94, v253, v94
	v_mul_f32_e32 v95, v253, v95
	v_cvt_pk_bf16_f32 v210, v92, v93
	v_cvt_pk_bf16_f32 v211, v94, v95
	global_store_dwordx2 v[244:245], v[210:211], off offset:64
	v_mul_f32_e32 v124, v253, v124
	v_mul_f32_e32 v125, v253, v125
	v_mul_f32_e32 v126, v253, v126
	v_mul_f32_e32 v127, v253, v127
	v_cvt_pk_bf16_f32 v212, v124, v125
	v_cvt_pk_bf16_f32 v213, v126, v127
	global_store_dwordx2 v[244:245], v[212:213], off offset:96
	s_add_i32 s11, s11, 1
	s_cmp_lt_u32 s11, 4
	s_cbranch_scc1 .Lg3_chunk
	s_mov_b32 s11, 0
	s_add_i32 s10, s10, s95
	s_cmpk_gt_i32 s10, 0x1ff
	s_cbranch_scc1 .Lg3_done
	v_and_b32_e32 v244, 15, v208
	v_lshlrev_b32_e32 v244, 2, v244
	s_lshl_b32 s2, s10, 9
	s_add_i32 s2, s2, 0x36c80000
	v_add_u32_e32 v244, s2, v244
	v_mov_b32_e32 v245, s93
	v_add_co_u32_e32 v244, vcc, s92, v244
	s_nop 1
	v_addc_co_u32_e32 v245, vcc, 0, v245, vcc
	global_load_dword v246, v[244:245], off
	global_load_dword v247, v[244:245], off offset:64
	global_load_dword v248, v[244:245], off offset:128
	global_load_dword v249, v[244:245], off offset:192
	global_load_dword v250, v[244:245], off offset:256
	global_load_dword v251, v[244:245], off offset:320
	global_load_dword v252, v[244:245], off offset:384
	global_load_dword v253, v[244:245], off offset:448
	s_branch .Lg3_chunk
